# v11 + GEMM5 epilogue: second residual batch and final-norm gains loaded together with the first batch
# baseline (speedup 1.0000x reference)
.LBB0_941:
	v_mbcnt_lo_u32_b32 v184, -1, 0
	v_mbcnt_hi_u32_b32 v184, -1, v184
	s_lshl_b32 s9, s34, 8
	v_ashrrev_i32_e32 v183, 3, v184
	v_add_u32_e32 v182, s60, v183
	v_add_u32_e32 v128, s9, v182
	v_ashrrev_i32_e32 v129, 31, v128
	s_lshl_b32 s36, s8, 8
	v_lshlrev_b64 v[128:129], 10, v[128:129]
	s_ashr_i32 s37, s36, 31
	v_lshl_add_u64 v[168:169], v[128:129], 0, s[36:37]
	v_or_b32_e32 v168, s66, v168
	v_lshlrev_b32_e32 v128, 4, v184
	v_and_b32_e32 v156, 0x70, v128
	v_lshl_add_u64 v[128:129], v[168:169], 1, s[12:13]
	v_lshl_add_u64 v[170:171], v[128:129], 0, v[156:157]
	v_add_co_u32_e32 v128, vcc, s55, v170
	v_mul_lo_u32 v183, v183, s71
	s_nop 0
	v_addc_co_u32_e32 v129, vcc, 0, v171, vcc
	global_load_dwordx4 v[186:189], v[170:171], off nt
	global_load_dwordx4 v[190:193], v[128:129], off nt
	v_add_co_u32_e32 v128, vcc, s64, v170
	v_add_u32_e32 v183, s70, v183
	s_nop 0
	v_addc_co_u32_e32 v129, vcc, 0, v171, vcc
	v_add_co_u32_e32 v130, vcc, s74, v170
	v_add_u32_e32 v183, v183, v156
	s_nop 0
	v_addc_co_u32_e32 v131, vcc, 0, v171, vcc
	v_add_co_u32_e32 v132, vcc, s53, v170
	v_add_u32_e32 v185, v174, v172
	s_nop 0
	v_addc_co_u32_e32 v133, vcc, 0, v171, vcc
	v_add_co_u32_e32 v134, vcc, s54, v170
	s_nop 1
	v_addc_co_u32_e32 v135, vcc, 0, v171, vcc
	v_add_co_u32_e32 v194, vcc, s63, v170
	s_nop 1
	v_addc_co_u32_e32 v195, vcc, 0, v171, vcc
	v_add_co_u32_e32 v196, vcc, s65, v170
	s_nop 1
	v_addc_co_u32_e32 v197, vcc, 0, v171, vcc
	global_load_dwordx4 v[144:147], v[128:129], off nt
	global_load_dwordx4 v[148:151], v[130:131], off nt
	global_load_dwordx4 v[136:139], v[132:133], off nt
	global_load_dwordx4 v[140:143], v[134:135], off nt
	s_nop 0
	global_load_dwordx4 v[128:131], v[194:195], off nt
	global_load_dwordx4 v[132:135], v[196:197], off nt
	s_mov_b32 s101, 0
	s_mov_b32 s100, 0x40000
	v_lshl_add_u64 v[234:235], v[170:171], 0, s[100:101]
	global_load_dwordx4 v[202:205], v[234:235], off nt
	s_mov_b32 s100, 0x44000
	v_lshl_add_u64 v[234:235], v[170:171], 0, s[100:101]
	global_load_dwordx4 v[206:209], v[234:235], off nt
	s_mov_b32 s100, 0x48000
	v_lshl_add_u64 v[234:235], v[170:171], 0, s[100:101]
	global_load_dwordx4 v[210:213], v[234:235], off nt
	s_mov_b32 s100, 0x4c000
	v_lshl_add_u64 v[234:235], v[170:171], 0, s[100:101]
	global_load_dwordx4 v[214:217], v[234:235], off nt
	s_mov_b32 s100, 0x50000
	v_lshl_add_u64 v[234:235], v[170:171], 0, s[100:101]
	global_load_dwordx4 v[218:221], v[234:235], off nt
	s_mov_b32 s100, 0x54000
	v_lshl_add_u64 v[234:235], v[170:171], 0, s[100:101]
	global_load_dwordx4 v[222:225], v[234:235], off nt
	s_mov_b32 s100, 0x58000
	v_lshl_add_u64 v[234:235], v[170:171], 0, s[100:101]
	global_load_dwordx4 v[226:229], v[234:235], off nt
	s_mov_b32 s100, 0x5c000
	v_lshl_add_u64 v[234:235], v[170:171], 0, s[100:101]
	global_load_dwordx4 v[230:233], v[234:235], off nt
	s_lshl_b64 s[98:99], s[36:37], 2
	s_add_u32 s98, s68, s98
	s_addc_u32 s99, s69, s99
	v_lshlrev_b32_e32 v244, 2, v184
	v_and_b32_e32 v244, 28, v244
	v_lshlrev_b32_e32 v244, 2, v244
	global_load_dwordx4 v[236:239], v244, s[98:99]
	global_load_dwordx4 v[240:243], v244, s[98:99] offset:128
	s_waitcnt vmcnt(0)
	ds_write_b128 v183, v[186:189]
	ds_write_b128 v183, v[190:193] offset:1152
	ds_read_b128 v[186:189], v185
	ds_read_b128 v[190:193], v185 offset:64
	s_waitcnt lgkmcnt(1)
	v_lshlrev_b32_e32 v194, 16, v186
	v_and_b32_e32 v195, 0xffff0000, v186
	v_lshlrev_b32_e32 v186, 16, v187
	v_and_b32_e32 v187, 0xffff0000, v187
	v_lshlrev_b32_e32 v196, 16, v188
	v_and_b32_e32 v197, 0xffff0000, v188
	v_lshlrev_b32_e32 v188, 16, v189
	v_and_b32_e32 v189, 0xffff0000, v189
	s_waitcnt lgkmcnt(0)
	v_lshlrev_b32_e32 v198, 16, v190
	v_and_b32_e32 v199, 0xffff0000, v190
	v_lshlrev_b32_e32 v190, 16, v191
	v_and_b32_e32 v191, 0xffff0000, v191
	v_lshlrev_b32_e32 v200, 16, v192
	v_and_b32_e32 v201, 0xffff0000, v192
	v_lshlrev_b32_e32 v192, 16, v193
	v_and_b32_e32 v193, 0xffff0000, v193
	v_pk_add_f32 v[124:125], v[124:125], v[194:195]
	v_pk_add_f32 v[126:127], v[126:127], v[186:187]
	v_pk_add_f32 v[120:121], v[120:121], v[196:197]
	v_pk_add_f32 v[122:123], v[122:123], v[188:189]
	v_pk_add_f32 v[108:109], v[108:109], v[198:199]
	v_pk_add_f32 v[110:111], v[110:111], v[190:191]
	v_pk_add_f32 v[100:101], v[100:101], v[200:201]
	v_pk_add_f32 v[102:103], v[102:103], v[192:193]
	v_pk_mul_f32 v[186:187], v[124:125], v[124:125]
	v_pk_mul_f32 v[188:189], v[126:127], v[126:127]
	v_pk_mul_f32 v[190:191], v[120:121], v[120:121]
	v_pk_mul_f32 v[192:193], v[122:123], v[122:123]
	v_pk_mul_f32 v[194:195], v[108:109], v[108:109]
	v_pk_mul_f32 v[196:197], v[110:111], v[110:111]
	v_pk_mul_f32 v[198:199], v[100:101], v[100:101]
	v_pk_mul_f32 v[200:201], v[102:103], v[102:103]
	v_add_f32_e32 v198, v198, v199
	v_add_f32_e32 v156, v200, v201
	v_add_f32_e32 v196, v196, v197
	v_add_f32_e32 v194, v194, v195
	v_add_f32_e32 v192, v192, v193
	v_add_f32_e32 v190, v190, v191
	v_add_f32_e32 v188, v188, v189
	v_add_f32_e32 v186, v186, v187
	v_add_f32_e32 v156, v198, v156
	v_add_f32_e32 v187, v194, v196
	v_add_f32_e32 v189, v190, v192
	v_add_f32_e32 v186, v186, v188
	v_add_f32_e32 v156, v187, v156
	v_add_f32_e32 v186, v186, v189
	v_and_b32_e32 v187, 64, v178
	v_add_f32_e32 v186, v186, v156
	v_add_u32_e32 v188, 64, v187
	v_mov_b32_e32 v187, v186
	s_nop 1
	v_permlane16_swap_b32_e32 v186, v187
	s_waitcnt lgkmcnt(0)
	v_add_f32_e32 v187, v186, v187
	v_xor_b32_e32 v186, 32, v178
	v_cmp_lt_i32_e32 vcc, v186, v188
	s_nop 1
	v_cndmask_b32_e32 v186, v178, v186, vcc
	v_lshlrev_b32_e32 v186, 2, v186
	v_mov_b32_e32 v188, v187
	s_nop 1
	v_permlane32_swap_b32_e32 v187, v188
	s_and_saveexec_b64 s[6:7], s[0:1]
	s_cbranch_execz .LBB0_943
	s_waitcnt lgkmcnt(0)
	v_add_f32_e32 v187, v187, v188
	ds_write_b32 v180, v187

.LBB0_949:
	s_or_b64 exec, exec, s[6:7]
	v_add_co_u32_e32 v128, vcc, 0x40000, v170
	s_waitcnt lgkmcnt(0)
	s_nop 0
	v_addc_co_u32_e32 v129, vcc, 0, v171, vcc
	v_add_co_u32_e32 v130, vcc, 0x44000, v170
	s_nop 1
	v_addc_co_u32_e32 v131, vcc, 0, v171, vcc
	v_mov_b64_e32 v[188:189], v[202:203]
	v_mov_b64_e32 v[190:191], v[204:205]
	v_mov_b64_e32 v[192:193], v[206:207]
	v_mov_b64_e32 v[194:195], v[208:209]
	v_add_co_u32_e32 v128, vcc, 0x48000, v170
	s_nop 1
	v_addc_co_u32_e32 v129, vcc, 0, v171, vcc
	v_add_co_u32_e32 v130, vcc, 0x4c000, v170
	s_nop 1
	v_addc_co_u32_e32 v131, vcc, 0, v171, vcc
	v_add_co_u32_e32 v132, vcc, 0x50000, v170
	v_mov_b64_e32 v[144:145], v[210:211]
	v_mov_b64_e32 v[146:147], v[212:213]
	v_mov_b64_e32 v[148:149], v[214:215]
	v_mov_b64_e32 v[150:151], v[216:217]
	v_addc_co_u32_e32 v133, vcc, 0, v171, vcc
	v_add_co_u32_e32 v128, vcc, 0x54000, v170
	s_nop 1
	v_addc_co_u32_e32 v129, vcc, 0, v171, vcc
	v_add_co_u32_e32 v130, vcc, 0x58000, v170
	v_mov_b64_e32 v[136:137], v[218:219]
	v_mov_b64_e32 v[138:139], v[220:221]
	v_mov_b64_e32 v[140:141], v[222:223]
	v_mov_b64_e32 v[142:143], v[224:225]
	v_addc_co_u32_e32 v131, vcc, 0, v171, vcc
	v_add_co_u32_e32 v132, vcc, 0x5c000, v170
	s_nop 1
	v_addc_co_u32_e32 v133, vcc, 0, v171, vcc
	v_mov_b64_e32 v[128:129], v[226:227]
	v_mov_b64_e32 v[130:131], v[228:229]
	s_nop 0
	v_mov_b64_e32 v[132:133], v[230:231]
	v_mov_b64_e32 v[134:135], v[232:233]
	s_waitcnt vmcnt(7)
	ds_write_b128 v183, v[188:191]
	s_waitcnt vmcnt(6)
	ds_write_b128 v183, v[192:195] offset:1152
	ds_read_b128 v[188:191], v185
	ds_read_b128 v[192:195], v185 offset:64
	s_waitcnt lgkmcnt(1)
	v_lshlrev_b32_e32 v170, 16, v188
	v_and_b32_e32 v171, 0xffff0000, v188
	v_lshlrev_b32_e32 v188, 16, v189
	v_and_b32_e32 v189, 0xffff0000, v189
	v_lshlrev_b32_e32 v196, 16, v190
	v_and_b32_e32 v197, 0xffff0000, v190
	v_lshlrev_b32_e32 v190, 16, v191
	v_and_b32_e32 v191, 0xffff0000, v191
	s_waitcnt lgkmcnt(0)
	v_lshlrev_b32_e32 v198, 16, v192
	v_and_b32_e32 v199, 0xffff0000, v192
	v_lshlrev_b32_e32 v192, 16, v193
	v_and_b32_e32 v193, 0xffff0000, v193
	v_lshlrev_b32_e32 v200, 16, v194
	v_and_b32_e32 v201, 0xffff0000, v194
	v_lshlrev_b32_e32 v194, 16, v195
	v_and_b32_e32 v195, 0xffff0000, v195
	v_pk_add_f32 v[60:61], v[60:61], v[170:171]
	v_pk_add_f32 v[62:63], v[62:63], v[188:189]
	v_pk_add_f32 v[56:57], v[56:57], v[196:197]
	v_pk_add_f32 v[58:59], v[58:59], v[190:191]
	v_pk_add_f32 v[52:53], v[52:53], v[198:199]
	v_pk_add_f32 v[54:55], v[54:55], v[192:193]
	v_pk_add_f32 v[48:49], v[48:49], v[200:201]
	v_pk_add_f32 v[50:51], v[50:51], v[194:195]
	v_pk_mul_f32 v[170:171], v[60:61], v[60:61]
	v_pk_mul_f32 v[188:189], v[62:63], v[62:63]
	v_pk_mul_f32 v[190:191], v[56:57], v[56:57]
	v_pk_mul_f32 v[192:193], v[58:59], v[58:59]
	v_pk_mul_f32 v[194:195], v[52:53], v[52:53]
	v_pk_mul_f32 v[196:197], v[54:55], v[54:55]
	v_pk_mul_f32 v[198:199], v[48:49], v[48:49]
	v_pk_mul_f32 v[200:201], v[50:51], v[50:51]
	v_add_f32_e32 v198, v198, v199
	v_add_f32_e32 v187, v200, v201
	v_add_f32_e32 v196, v196, v197
	v_add_f32_e32 v194, v194, v195
	v_add_f32_e32 v192, v192, v193
	v_add_f32_e32 v190, v190, v191
	v_add_f32_e32 v188, v188, v189
	v_add_f32_e32 v170, v170, v171
	v_add_f32_e32 v187, v198, v187
	v_add_f32_e32 v191, v194, v196
	v_add_f32_e32 v190, v190, v192
	v_add_f32_e32 v170, v170, v188
	v_add_f32_e32 v187, v191, v187
	v_add_f32_e32 v170, v170, v190
	v_add_f32_e32 v170, v170, v187
	v_mov_b32_e32 v171, v170
	s_nop 1
	v_permlane16_swap_b32_e32 v170, v171
	s_waitcnt lgkmcnt(0)
	v_add_f32_e32 v170, v170, v171
	v_mov_b32_e32 v171, v170
	s_nop 1
	v_permlane32_swap_b32_e32 v170, v171
	s_and_saveexec_b64 s[6:7], s[0:1]
	s_cbranch_execz .LBB0_951
	s_waitcnt lgkmcnt(0)
	v_add_f32_e32 v170, v170, v171
	ds_write_b32 v180, v170 offset:2048

.LBB0_974:
	s_or_b64 exec, exec, s[8:9]
	s_lshl_b64 s[6:7], s[36:37], 2
	v_lshlrev_b32_e32 v128, 2, v184
	s_add_u32 s6, s68, s6
	v_and_b32_e32 v128, 28, v128
	s_addc_u32 s7, s69, s7
	s_waitcnt vmcnt(0) lgkmcnt(0)
	s_barrier
	v_lshlrev_b32_e32 v156, 2, v128
	v_mov_b64_e32 v[132:133], v[236:237]
	v_mov_b64_e32 v[134:135], v[238:239]
	v_mov_b64_e32 v[128:129], v[240:241]
	v_mov_b64_e32 v[130:131], v[242:243]
	s_waitcnt lgkmcnt(0)
	v_cmp_ne_u32_e32 vcc, 0, v136
	v_cmp_eq_u32_e64 s[8:9], 0, v136
	v_mov_b32_e32 v136, 0x7fc00000
	v_mov_b32_e32 v138, 0x7fc00000
	s_cbranch_vccz .LBB0_993
	v_cndmask_b32_e64 v137, 0, 1, s[8:9]
	v_cmp_ne_u32_e64 s[6:7], 1, v137
	s_andn2_b64 vcc, exec, s[8:9]
	s_cbranch_vccz .LBB0_994
